# P6/P9 residual epilogue: all 32 residual loads (16 in flight) and adds first, then the 32 stores (separates the HBM read and write phases of the burst)
# speedup vs baseline: 1.0241x; 1.0002x over previous
.LBB0_1386:
	v_readlane_b32 s16, v251, 41
	v_readlane_b32 s17, v251, 42
	v_lshl_add_u32 v138, s31, 8, v140
	v_lshl_or_b32 v136, s30, 8, v142
	v_lshlrev_b32_e32 v134, 13, v138
	v_lshl_add_u32 v134, v136, 2, v134
	v_add_u32_e32 v135, 0x20000, v134
	v_add_u32_e32 v137, 0x40000, v134
	v_add_u32_e32 v139, 0x60000, v134
	v_add_u32_e32 v144, 0x100000, v134
	v_add_u32_e32 v145, 0x120000, v134
	v_add_u32_e32 v146, 0x140000, v134
	v_add_u32_e32 v147, 0x160000, v134
	global_load_dwordx4 v[162:165], v134, s[16:17]
	global_load_dwordx4 v[166:169], v134, s[16:17] offset:64
	global_load_dwordx4 v[170:173], v134, s[16:17] offset:512
	global_load_dwordx4 v[174:177], v134, s[16:17] offset:576
	global_load_dwordx4 v[178:181], v135, s[16:17]
	global_load_dwordx4 v[182:185], v135, s[16:17] offset:64
	global_load_dwordx4 v[186:189], v135, s[16:17] offset:512
	global_load_dwordx4 v[190:193], v135, s[16:17] offset:576
	global_load_dwordx4 v[194:197], v137, s[16:17]
	global_load_dwordx4 v[198:201], v137, s[16:17] offset:64
	global_load_dwordx4 v[202:205], v137, s[16:17] offset:512
	global_load_dwordx4 v[214:217], v137, s[16:17] offset:576
	global_load_dwordx4 v[218:221], v139, s[16:17]
	global_load_dwordx4 v[222:225], v139, s[16:17] offset:64
	global_load_dwordx4 v[226:229], v139, s[16:17] offset:512
	global_load_dwordx4 v[230:233], v139, s[16:17] offset:576
	s_waitcnt vmcnt(15)
	v_pk_add_f32 v[126:127], v[126:127], v[164:165]
	v_pk_add_f32 v[124:125], v[124:125], v[162:163]
	global_load_dwordx4 v[162:165], v144, s[16:17]
	s_waitcnt vmcnt(15)
	v_pk_add_f32 v[122:123], v[122:123], v[168:169]
	v_pk_add_f32 v[120:121], v[120:121], v[166:167]
	global_load_dwordx4 v[166:169], v144, s[16:17] offset:64
	s_waitcnt vmcnt(15)
	v_pk_add_f32 v[118:119], v[118:119], v[172:173]
	v_pk_add_f32 v[116:117], v[116:117], v[170:171]
	global_load_dwordx4 v[170:173], v144, s[16:17] offset:512
	s_waitcnt vmcnt(15)
	v_pk_add_f32 v[114:115], v[114:115], v[176:177]
	v_pk_add_f32 v[112:113], v[112:113], v[174:175]
	global_load_dwordx4 v[174:177], v144, s[16:17] offset:576
	s_waitcnt vmcnt(15)
	v_pk_add_f32 v[110:111], v[110:111], v[180:181]
	v_pk_add_f32 v[108:109], v[108:109], v[178:179]
	global_load_dwordx4 v[178:181], v145, s[16:17]
	s_waitcnt vmcnt(15)
	v_pk_add_f32 v[106:107], v[106:107], v[184:185]
	v_pk_add_f32 v[104:105], v[104:105], v[182:183]
	global_load_dwordx4 v[182:185], v145, s[16:17] offset:64
	s_waitcnt vmcnt(15)
	v_pk_add_f32 v[102:103], v[102:103], v[188:189]
	v_pk_add_f32 v[100:101], v[100:101], v[186:187]
	global_load_dwordx4 v[186:189], v145, s[16:17] offset:512
	s_waitcnt vmcnt(15)
	v_pk_add_f32 v[98:99], v[98:99], v[192:193]
	v_pk_add_f32 v[96:97], v[96:97], v[190:191]
	global_load_dwordx4 v[190:193], v145, s[16:17] offset:576
	s_waitcnt vmcnt(15)
	v_pk_add_f32 v[94:95], v[94:95], v[196:197]
	v_pk_add_f32 v[92:93], v[92:93], v[194:195]
	global_load_dwordx4 v[194:197], v146, s[16:17]
	s_waitcnt vmcnt(15)
	v_pk_add_f32 v[90:91], v[90:91], v[200:201]
	v_pk_add_f32 v[88:89], v[88:89], v[198:199]
	global_load_dwordx4 v[198:201], v146, s[16:17] offset:64
	s_waitcnt vmcnt(15)
	v_pk_add_f32 v[86:87], v[86:87], v[204:205]
	v_pk_add_f32 v[84:85], v[84:85], v[202:203]
	global_load_dwordx4 v[202:205], v146, s[16:17] offset:512
	s_waitcnt vmcnt(15)
	v_pk_add_f32 v[82:83], v[82:83], v[216:217]
	v_pk_add_f32 v[80:81], v[80:81], v[214:215]
	global_load_dwordx4 v[214:217], v146, s[16:17] offset:576
	s_waitcnt vmcnt(15)
	v_pk_add_f32 v[78:79], v[78:79], v[220:221]
	v_pk_add_f32 v[76:77], v[76:77], v[218:219]
	global_load_dwordx4 v[218:221], v147, s[16:17]
	s_waitcnt vmcnt(15)
	v_pk_add_f32 v[74:75], v[74:75], v[224:225]
	v_pk_add_f32 v[72:73], v[72:73], v[222:223]
	global_load_dwordx4 v[222:225], v147, s[16:17] offset:64
	s_waitcnt vmcnt(15)
	v_pk_add_f32 v[70:71], v[70:71], v[228:229]
	v_pk_add_f32 v[68:69], v[68:69], v[226:227]
	global_load_dwordx4 v[226:229], v147, s[16:17] offset:512
	s_waitcnt vmcnt(15)
	v_pk_add_f32 v[66:67], v[66:67], v[232:233]
	v_pk_add_f32 v[64:65], v[64:65], v[230:231]
	global_load_dwordx4 v[230:233], v147, s[16:17] offset:576
	s_waitcnt vmcnt(15)
	v_pk_add_f32 v[62:63], v[62:63], v[164:165]
	v_pk_add_f32 v[60:61], v[60:61], v[162:163]
	s_waitcnt vmcnt(14)
	v_pk_add_f32 v[58:59], v[58:59], v[168:169]
	v_pk_add_f32 v[56:57], v[56:57], v[166:167]
	s_waitcnt vmcnt(13)
	v_pk_add_f32 v[54:55], v[54:55], v[172:173]
	v_pk_add_f32 v[52:53], v[52:53], v[170:171]
	s_waitcnt vmcnt(12)
	v_pk_add_f32 v[50:51], v[50:51], v[176:177]
	v_pk_add_f32 v[48:49], v[48:49], v[174:175]
	s_waitcnt vmcnt(11)
	v_pk_add_f32 v[46:47], v[46:47], v[180:181]
	v_pk_add_f32 v[44:45], v[44:45], v[178:179]
	s_waitcnt vmcnt(10)
	v_pk_add_f32 v[42:43], v[42:43], v[184:185]
	v_pk_add_f32 v[40:41], v[40:41], v[182:183]
	s_waitcnt vmcnt(9)
	v_pk_add_f32 v[38:39], v[38:39], v[188:189]
	v_pk_add_f32 v[36:37], v[36:37], v[186:187]
	s_waitcnt vmcnt(8)
	v_pk_add_f32 v[34:35], v[34:35], v[192:193]
	v_pk_add_f32 v[32:33], v[32:33], v[190:191]
	s_waitcnt vmcnt(7)
	v_pk_add_f32 v[30:31], v[30:31], v[196:197]
	v_pk_add_f32 v[28:29], v[28:29], v[194:195]
	s_waitcnt vmcnt(6)
	v_pk_add_f32 v[26:27], v[26:27], v[200:201]
	v_pk_add_f32 v[24:25], v[24:25], v[198:199]
	s_waitcnt vmcnt(5)
	v_pk_add_f32 v[22:23], v[22:23], v[204:205]
	v_pk_add_f32 v[20:21], v[20:21], v[202:203]
	s_waitcnt vmcnt(4)
	v_pk_add_f32 v[18:19], v[18:19], v[216:217]
	v_pk_add_f32 v[16:17], v[16:17], v[214:215]
	s_waitcnt vmcnt(3)
	v_pk_add_f32 v[14:15], v[14:15], v[220:221]
	v_pk_add_f32 v[12:13], v[12:13], v[218:219]
	s_waitcnt vmcnt(2)
	v_pk_add_f32 v[10:11], v[10:11], v[224:225]
	v_pk_add_f32 v[8:9], v[8:9], v[222:223]
	s_waitcnt vmcnt(1)
	v_pk_add_f32 v[6:7], v[6:7], v[228:229]
	v_pk_add_f32 v[4:5], v[4:5], v[226:227]
	s_waitcnt vmcnt(0)
	v_pk_add_f32 v[2:3], v[2:3], v[232:233]
	v_pk_add_f32 v[0:1], v[0:1], v[230:231]
	global_store_dwordx4 v134, v[124:127], s[52:53]
	global_store_dwordx4 v134, v[120:123], s[52:53] offset:64
	global_store_dwordx4 v134, v[116:119], s[52:53] offset:512
	global_store_dwordx4 v134, v[112:115], s[52:53] offset:576
	global_store_dwordx4 v135, v[108:111], s[52:53]
	global_store_dwordx4 v135, v[104:107], s[52:53] offset:64
	global_store_dwordx4 v135, v[100:103], s[52:53] offset:512
	global_store_dwordx4 v135, v[96:99], s[52:53] offset:576
	global_store_dwordx4 v137, v[92:95], s[52:53]
	global_store_dwordx4 v137, v[88:91], s[52:53] offset:64
	global_store_dwordx4 v137, v[84:87], s[52:53] offset:512
	global_store_dwordx4 v137, v[80:83], s[52:53] offset:576
	global_store_dwordx4 v139, v[76:79], s[52:53]
	global_store_dwordx4 v139, v[72:75], s[52:53] offset:64
	global_store_dwordx4 v139, v[68:71], s[52:53] offset:512
	global_store_dwordx4 v139, v[64:67], s[52:53] offset:576
	global_store_dwordx4 v144, v[60:63], s[52:53]
	global_store_dwordx4 v144, v[56:59], s[52:53] offset:64
	global_store_dwordx4 v144, v[52:55], s[52:53] offset:512
	global_store_dwordx4 v144, v[48:51], s[52:53] offset:576
	global_store_dwordx4 v145, v[44:47], s[52:53]
	global_store_dwordx4 v145, v[40:43], s[52:53] offset:64
	global_store_dwordx4 v145, v[36:39], s[52:53] offset:512
	global_store_dwordx4 v145, v[32:35], s[52:53] offset:576
	global_store_dwordx4 v146, v[28:31], s[52:53]
	global_store_dwordx4 v146, v[24:27], s[52:53] offset:64
	global_store_dwordx4 v146, v[20:23], s[52:53] offset:512
	global_store_dwordx4 v146, v[16:19], s[52:53] offset:576
	global_store_dwordx4 v147, v[12:15], s[52:53]
	global_store_dwordx4 v147, v[8:11], s[52:53] offset:64
	global_store_dwordx4 v147, v[4:7], s[52:53] offset:512
	global_store_dwordx4 v147, v[0:3], s[52:53] offset:576
	s_mov_b64 s[14:15], -1
	s_andn2_b64 vcc, exec, s[0:1]
	s_cbranch_vccnz .LBB0_1375
	s_andn2_b64 vcc, exec, s[2:3]
	s_cbranch_vccnz .LBB0_1374
	s_barrier
	s_branch .LBB0_1374

.LBB0_1593:
	v_lshl_add_u32 v138, s29, 8, v140
	v_lshl_or_b32 v136, s28, 8, v142
	v_lshlrev_b32_e32 v134, 13, v138
	v_lshl_add_u32 v134, v136, 2, v134
	v_add_u32_e32 v135, 0x20000, v134
	v_add_u32_e32 v137, 0x40000, v134
	v_add_u32_e32 v139, 0x60000, v134
	v_add_u32_e32 v144, 0x100000, v134
	v_add_u32_e32 v145, 0x120000, v134
	v_add_u32_e32 v146, 0x140000, v134
	v_add_u32_e32 v147, 0x160000, v134
	global_load_dwordx4 v[162:165], v134, s[52:53]
	global_load_dwordx4 v[166:169], v134, s[52:53] offset:64
	global_load_dwordx4 v[170:173], v134, s[52:53] offset:512
	global_load_dwordx4 v[174:177], v134, s[52:53] offset:576
	global_load_dwordx4 v[178:181], v135, s[52:53]
	global_load_dwordx4 v[182:185], v135, s[52:53] offset:64
	global_load_dwordx4 v[186:189], v135, s[52:53] offset:512
	global_load_dwordx4 v[190:193], v135, s[52:53] offset:576
	global_load_dwordx4 v[194:197], v137, s[52:53]
	global_load_dwordx4 v[198:201], v137, s[52:53] offset:64
	global_load_dwordx4 v[202:205], v137, s[52:53] offset:512
	global_load_dwordx4 v[214:217], v137, s[52:53] offset:576
	global_load_dwordx4 v[218:221], v139, s[52:53]
	global_load_dwordx4 v[222:225], v139, s[52:53] offset:64
	global_load_dwordx4 v[226:229], v139, s[52:53] offset:512
	global_load_dwordx4 v[230:233], v139, s[52:53] offset:576
	s_waitcnt vmcnt(15)
	v_pk_add_f32 v[126:127], v[126:127], v[164:165]
	v_pk_add_f32 v[124:125], v[124:125], v[162:163]
	global_load_dwordx4 v[162:165], v144, s[52:53]
	s_waitcnt vmcnt(15)
	v_pk_add_f32 v[122:123], v[122:123], v[168:169]
	v_pk_add_f32 v[120:121], v[120:121], v[166:167]
	global_load_dwordx4 v[166:169], v144, s[52:53] offset:64
	s_waitcnt vmcnt(15)
	v_pk_add_f32 v[118:119], v[118:119], v[172:173]
	v_pk_add_f32 v[116:117], v[116:117], v[170:171]
	global_load_dwordx4 v[170:173], v144, s[52:53] offset:512
	s_waitcnt vmcnt(15)
	v_pk_add_f32 v[114:115], v[114:115], v[176:177]
	v_pk_add_f32 v[112:113], v[112:113], v[174:175]
	global_load_dwordx4 v[174:177], v144, s[52:53] offset:576
	s_waitcnt vmcnt(15)
	v_pk_add_f32 v[110:111], v[110:111], v[180:181]
	v_pk_add_f32 v[108:109], v[108:109], v[178:179]
	global_load_dwordx4 v[178:181], v145, s[52:53]
	s_waitcnt vmcnt(15)
	v_pk_add_f32 v[106:107], v[106:107], v[184:185]
	v_pk_add_f32 v[104:105], v[104:105], v[182:183]
	global_load_dwordx4 v[182:185], v145, s[52:53] offset:64
	s_waitcnt vmcnt(15)
	v_pk_add_f32 v[102:103], v[102:103], v[188:189]
	v_pk_add_f32 v[100:101], v[100:101], v[186:187]
	global_load_dwordx4 v[186:189], v145, s[52:53] offset:512
	s_waitcnt vmcnt(15)
	v_pk_add_f32 v[98:99], v[98:99], v[192:193]
	v_pk_add_f32 v[96:97], v[96:97], v[190:191]
	global_load_dwordx4 v[190:193], v145, s[52:53] offset:576
	s_waitcnt vmcnt(15)
	v_pk_add_f32 v[94:95], v[94:95], v[196:197]
	v_pk_add_f32 v[92:93], v[92:93], v[194:195]
	global_load_dwordx4 v[194:197], v146, s[52:53]
	s_waitcnt vmcnt(15)
	v_pk_add_f32 v[90:91], v[90:91], v[200:201]
	v_pk_add_f32 v[88:89], v[88:89], v[198:199]
	global_load_dwordx4 v[198:201], v146, s[52:53] offset:64
	s_waitcnt vmcnt(15)
	v_pk_add_f32 v[86:87], v[86:87], v[204:205]
	v_pk_add_f32 v[84:85], v[84:85], v[202:203]
	global_load_dwordx4 v[202:205], v146, s[52:53] offset:512
	s_waitcnt vmcnt(15)
	v_pk_add_f32 v[82:83], v[82:83], v[216:217]
	v_pk_add_f32 v[80:81], v[80:81], v[214:215]
	global_load_dwordx4 v[214:217], v146, s[52:53] offset:576
	s_waitcnt vmcnt(15)
	v_pk_add_f32 v[78:79], v[78:79], v[220:221]
	v_pk_add_f32 v[76:77], v[76:77], v[218:219]
	global_load_dwordx4 v[218:221], v147, s[52:53]
	s_waitcnt vmcnt(15)
	v_pk_add_f32 v[74:75], v[74:75], v[224:225]
	v_pk_add_f32 v[72:73], v[72:73], v[222:223]
	global_load_dwordx4 v[222:225], v147, s[52:53] offset:64
	s_waitcnt vmcnt(15)
	v_pk_add_f32 v[70:71], v[70:71], v[228:229]
	v_pk_add_f32 v[68:69], v[68:69], v[226:227]
	global_load_dwordx4 v[226:229], v147, s[52:53] offset:512
	s_waitcnt vmcnt(15)
	v_pk_add_f32 v[66:67], v[66:67], v[232:233]
	v_pk_add_f32 v[64:65], v[64:65], v[230:231]
	global_load_dwordx4 v[230:233], v147, s[52:53] offset:576
	s_waitcnt vmcnt(15)
	v_pk_add_f32 v[62:63], v[62:63], v[164:165]
	v_pk_add_f32 v[60:61], v[60:61], v[162:163]
	s_waitcnt vmcnt(14)
	v_pk_add_f32 v[58:59], v[58:59], v[168:169]
	v_pk_add_f32 v[56:57], v[56:57], v[166:167]
	s_waitcnt vmcnt(13)
	v_pk_add_f32 v[54:55], v[54:55], v[172:173]
	v_pk_add_f32 v[52:53], v[52:53], v[170:171]
	s_waitcnt vmcnt(12)
	v_pk_add_f32 v[50:51], v[50:51], v[176:177]
	v_pk_add_f32 v[48:49], v[48:49], v[174:175]
	s_waitcnt vmcnt(11)
	v_pk_add_f32 v[46:47], v[46:47], v[180:181]
	v_pk_add_f32 v[44:45], v[44:45], v[178:179]
	s_waitcnt vmcnt(10)
	v_pk_add_f32 v[42:43], v[42:43], v[184:185]
	v_pk_add_f32 v[40:41], v[40:41], v[182:183]
	s_waitcnt vmcnt(9)
	v_pk_add_f32 v[38:39], v[38:39], v[188:189]
	v_pk_add_f32 v[36:37], v[36:37], v[186:187]
	s_waitcnt vmcnt(8)
	v_pk_add_f32 v[34:35], v[34:35], v[192:193]
	v_pk_add_f32 v[32:33], v[32:33], v[190:191]
	s_waitcnt vmcnt(7)
	v_pk_add_f32 v[30:31], v[30:31], v[196:197]
	v_pk_add_f32 v[28:29], v[28:29], v[194:195]
	s_waitcnt vmcnt(6)
	v_pk_add_f32 v[26:27], v[26:27], v[200:201]
	v_pk_add_f32 v[24:25], v[24:25], v[198:199]
	s_waitcnt vmcnt(5)
	v_pk_add_f32 v[22:23], v[22:23], v[204:205]
	v_pk_add_f32 v[20:21], v[20:21], v[202:203]
	s_waitcnt vmcnt(4)
	v_pk_add_f32 v[18:19], v[18:19], v[216:217]
	v_pk_add_f32 v[16:17], v[16:17], v[214:215]
	s_waitcnt vmcnt(3)
	v_pk_add_f32 v[14:15], v[14:15], v[220:221]
	v_pk_add_f32 v[12:13], v[12:13], v[218:219]
	s_waitcnt vmcnt(2)
	v_pk_add_f32 v[10:11], v[10:11], v[224:225]
	v_pk_add_f32 v[8:9], v[8:9], v[222:223]
	s_waitcnt vmcnt(1)
	v_pk_add_f32 v[6:7], v[6:7], v[228:229]
	v_pk_add_f32 v[4:5], v[4:5], v[226:227]
	s_waitcnt vmcnt(0)
	v_pk_add_f32 v[2:3], v[2:3], v[232:233]
	v_pk_add_f32 v[0:1], v[0:1], v[230:231]
	global_store_dwordx4 v134, v[124:127], s[52:53]
	global_store_dwordx4 v134, v[120:123], s[52:53] offset:64
	global_store_dwordx4 v134, v[116:119], s[52:53] offset:512
	global_store_dwordx4 v134, v[112:115], s[52:53] offset:576
	global_store_dwordx4 v135, v[108:111], s[52:53]
	global_store_dwordx4 v135, v[104:107], s[52:53] offset:64
	global_store_dwordx4 v135, v[100:103], s[52:53] offset:512
	global_store_dwordx4 v135, v[96:99], s[52:53] offset:576
	global_store_dwordx4 v137, v[92:95], s[52:53]
	global_store_dwordx4 v137, v[88:91], s[52:53] offset:64
	global_store_dwordx4 v137, v[84:87], s[52:53] offset:512
	global_store_dwordx4 v137, v[80:83], s[52:53] offset:576
	global_store_dwordx4 v139, v[76:79], s[52:53]
	global_store_dwordx4 v139, v[72:75], s[52:53] offset:64
	global_store_dwordx4 v139, v[68:71], s[52:53] offset:512
	global_store_dwordx4 v139, v[64:67], s[52:53] offset:576
	global_store_dwordx4 v144, v[60:63], s[52:53]
	global_store_dwordx4 v144, v[56:59], s[52:53] offset:64
	global_store_dwordx4 v144, v[52:55], s[52:53] offset:512
	global_store_dwordx4 v144, v[48:51], s[52:53] offset:576
	global_store_dwordx4 v145, v[44:47], s[52:53]
	global_store_dwordx4 v145, v[40:43], s[52:53] offset:64
	global_store_dwordx4 v145, v[36:39], s[52:53] offset:512
	global_store_dwordx4 v145, v[32:35], s[52:53] offset:576
	global_store_dwordx4 v146, v[28:31], s[52:53]
	global_store_dwordx4 v146, v[24:27], s[52:53] offset:64
	global_store_dwordx4 v146, v[20:23], s[52:53] offset:512
	global_store_dwordx4 v146, v[16:19], s[52:53] offset:576
	global_store_dwordx4 v147, v[12:15], s[52:53]
	global_store_dwordx4 v147, v[8:11], s[52:53] offset:64
	global_store_dwordx4 v147, v[4:7], s[52:53] offset:512
	global_store_dwordx4 v147, v[0:3], s[52:53] offset:576
	s_mov_b64 s[10:11], -1
	s_and_b64 vcc, exec, s[0:1]
	s_cbranch_vccnz .LBB0_1578
	s_andn2_b64 vcc, exec, s[4:5]
	s_cbranch_vccnz .LBB0_1577
	s_barrier
	s_branch .LBB0_1577
